# MLP-in epilogue: the eight row-scale loads are issued at tile start so the epilogue no longer drains the LDS-DMA prefetch of the next tile (vmcnt 0 -> 8)
# baseline (speedup 1.0000x reference)
; template <class Epi, class Sched, bool ALIGN_EPI = false, bool SP2 = false, bool FP8 = false>
; __device__ __forceinline__ void gemm_phase(PG8_LAS unsigned char* lds, const Gemm g, const Sched& S, const Epi& E, int wave_id) {
;     ...
;         for (int a = 0; a < 2; ++a)
; #pragma unroll
;             for (int b = 0; b < 2; ++b)
; #pragma unroll
;                 for (int m = 0; m < 4; ++m)
; #pragma unroll
;                     for (int n = 0; n < 2; ++n) acc[a][b][m][n] = (f32x4){0.f, 0.f, 0.f, 0.f};
;         cur = nxt; cA = nA; cB = nB; ++ui;
;     __device__ __forceinline__ void operator()(const f32x4 (&acc)[2][2][4][2], const Unit& u, int wr, int wc, int fr, int fq) const {
;         const int row0 = u.pm * BM + wr * 64 + fr, col0 = u.pn * BM + wc * 32 + 8 * fq;
;         float rs[2][4];
; #pragma unroll
;         for (int ai = 0; ai < 2; ++ai)
; #pragma unroll
;             for (int m = 0; m < 4; ++m) rs[ai][m] = __hip_atomic_load(ss + row0 + ai * HALF + m * 16, __ATOMIC_RELAXED, __HIP_MEMORY_SCOPE_AGENT);
;         asm volatile("" ::: "memory");
.LBB0_418:
	s_ashr_i32 s23, s22, 31
	v_cmp_lt_i64_e32 vcc, s[24:25], v[172:173]
	s_lshl_b64 s[24:25], s[22:23], 19
	s_add_u32 s24, s6, s24
	s_addc_u32 s25, s7, s25
	s_and_b64 s[26:27], vcc, exec
	s_cselect_b32 s23, s25, s31
	s_cselect_b32 s66, s24, s30
	s_ashr_i32 s21, s20, 31
	s_lshl_b64 s[26:27], s[20:21], 19
	s_add_u32 s26, s82, s26
	s_addc_u32 s27, s83, s27
	s_and_b64 s[36:37], vcc, exec
	s_cselect_b32 s21, s27, s35
	s_cselect_b32 s67, s26, s34
	s_add_u32 s30, s30, 0x40080
	s_addc_u32 s31, s31, 0
	s_add_u32 s69, s34, 0x100
	v_mov_b32_e32 v32, 0
	s_addc_u32 s71, s35, 0
	s_mov_b32 s74, -2
	v_mov_b32_e32 v33, v32
	v_mov_b32_e32 v34, v32
	v_mov_b32_e32 v35, v32
	v_mov_b32_e32 v36, v32
	v_mov_b32_e32 v37, v32
	v_mov_b32_e32 v38, v32
	v_mov_b32_e32 v39, v32
	v_mov_b32_e32 v48, v32
	v_mov_b32_e32 v49, v32
	v_mov_b32_e32 v50, v32
	v_mov_b32_e32 v51, v32
	v_mov_b32_e32 v52, v32
	v_mov_b32_e32 v53, v32
	v_mov_b32_e32 v54, v32
	v_mov_b32_e32 v55, v32
	v_mov_b32_e32 v64, v32
	v_mov_b32_e32 v65, v32
	v_mov_b32_e32 v66, v32
	v_mov_b32_e32 v67, v32
	v_mov_b32_e32 v68, v32
	v_mov_b32_e32 v69, v32
	v_mov_b32_e32 v70, v32
	v_mov_b32_e32 v71, v32
	v_mov_b32_e32 v80, v32
	v_mov_b32_e32 v81, v32
	v_mov_b32_e32 v82, v32
	v_mov_b32_e32 v83, v32
	v_mov_b32_e32 v84, v32
	v_mov_b32_e32 v85, v32
	v_mov_b32_e32 v86, v32
	v_mov_b32_e32 v87, v32
	v_mov_b32_e32 v40, v32
	v_mov_b32_e32 v41, v32
	v_mov_b32_e32 v42, v32
	v_mov_b32_e32 v43, v32
	v_mov_b32_e32 v44, v32
	v_mov_b32_e32 v45, v32
	v_mov_b32_e32 v46, v32
	v_mov_b32_e32 v47, v32
	v_mov_b32_e32 v56, v32
	v_mov_b32_e32 v57, v32
	v_mov_b32_e32 v58, v32
	v_mov_b32_e32 v59, v32
	v_mov_b32_e32 v60, v32
	v_mov_b32_e32 v61, v32
	v_mov_b32_e32 v62, v32
	v_mov_b32_e32 v63, v32
	v_mov_b32_e32 v72, v32
	v_mov_b32_e32 v73, v32
	v_mov_b32_e32 v74, v32
	v_mov_b32_e32 v75, v32
	v_mov_b32_e32 v76, v32
	v_mov_b32_e32 v77, v32
	v_mov_b32_e32 v78, v32
	v_mov_b32_e32 v79, v32
	v_mov_b32_e32 v88, v32
	v_mov_b32_e32 v89, v32
	v_mov_b32_e32 v90, v32
	v_mov_b32_e32 v91, v32
	v_mov_b32_e32 v92, v32
	v_mov_b32_e32 v93, v32
	v_mov_b32_e32 v94, v32
	v_mov_b32_e32 v95, v32
	v_mov_b32_e32 v96, v32
	v_mov_b32_e32 v97, v32
	v_mov_b32_e32 v98, v32
	v_mov_b32_e32 v99, v32
	v_mov_b32_e32 v100, v32
	v_mov_b32_e32 v101, v32
	v_mov_b32_e32 v102, v32
	v_mov_b32_e32 v103, v32
	v_mov_b32_e32 v112, v32
	v_mov_b32_e32 v113, v32
	v_mov_b32_e32 v114, v32
	v_mov_b32_e32 v115, v32
	v_mov_b32_e32 v116, v32
	v_mov_b32_e32 v117, v32
	v_mov_b32_e32 v118, v32
	v_mov_b32_e32 v119, v32
	v_mov_b32_e32 v128, v32
	v_mov_b32_e32 v129, v32
	v_mov_b32_e32 v130, v32
	v_mov_b32_e32 v131, v32
	v_mov_b32_e32 v132, v32
	v_mov_b32_e32 v133, v32
	v_mov_b32_e32 v134, v32
	v_mov_b32_e32 v135, v32
	v_mov_b32_e32 v140, v32
	v_mov_b32_e32 v141, v32
	v_mov_b32_e32 v142, v32
	v_mov_b32_e32 v143, v32
	v_mov_b32_e32 v144, v32
	v_mov_b32_e32 v145, v32
	v_mov_b32_e32 v146, v32
	v_mov_b32_e32 v147, v32
	v_mov_b32_e32 v104, v32
	v_mov_b32_e32 v105, v32
	v_mov_b32_e32 v106, v32
	v_mov_b32_e32 v107, v32
	v_mov_b32_e32 v108, v32
	v_mov_b32_e32 v109, v32
	v_mov_b32_e32 v110, v32
	v_mov_b32_e32 v111, v32
	v_mov_b32_e32 v120, v32
	v_mov_b32_e32 v121, v32
	v_mov_b32_e32 v122, v32
	v_mov_b32_e32 v123, v32
	v_mov_b32_e32 v124, v32
	v_mov_b32_e32 v125, v32
	v_mov_b32_e32 v126, v32
	v_mov_b32_e32 v127, v32
	v_mov_b32_e32 v136, v32
	v_mov_b32_e32 v137, v32
	v_mov_b32_e32 v138, v32
	v_mov_b32_e32 v139, v32
	v_mov_b32_e32 v148, v32
	v_mov_b32_e32 v149, v32
	v_mov_b32_e32 v150, v32
	v_mov_b32_e32 v151, v32
	v_mov_b32_e32 v152, v32
	v_mov_b32_e32 v153, v32
	v_mov_b32_e32 v154, v32
	v_mov_b32_e32 v155, v32
	v_mov_b32_e32 v156, v32
	v_mov_b32_e32 v157, v32
	v_mov_b32_e32 v158, v32
	v_mov_b32_e32 v159, v32
	v_lshl_add_u32 v234, s28, 8, v184
	v_ashrrev_i32_e32 v235, 31, v234
	v_lshl_add_u64 v[236:237], v[234:235], 2, s[8:9]
	global_load_dword v226, v[236:237], off sc1
	global_load_dword v227, v[236:237], off offset:64 sc1
	global_load_dword v228, v[236:237], off offset:128 sc1
	global_load_dword v229, v[236:237], off offset:192 sc1
	global_load_dword v230, v[236:237], off offset:512 sc1
	global_load_dword v231, v[236:237], off offset:576 sc1
	global_load_dword v232, v[236:237], off offset:640 sc1
	global_load_dword v233, v[236:237], off offset:704 sc1
; #define PG8_STAGE(bufoff, gbase, voff) do { _Pragma("unroll") for (int _i = 0; _i < 2; ++_i) \
;         __builtin_amdgcn_global_load_lds((const unsigned*)((const char*)(gbase) + (voff)[_i]), (PG8_LAS unsigned*)(lds + (bufoff) + ldsw + _i * 8192), 16, 0, 0); } while (0)
; #define PG8_LDA(dst, b, h) do { _Pragma("unroll") for (int m = 0; m < 4; ++m) { if constexpr (FP8) dst##8[m] = PG8_LD32(lds + PG8_SA(b, h) + aoff + m * 2048); else { _Pragma("unroll") for (int k = 0; k < 2; ++k) dst[m][k] = *(const PG8_LAS bf16x8*)(lds + PG8_SA(b, h) + aoff + m * 2048 + k * 1024); } } } while (0)
; #define PG8_LDB(dst, b, h) do { _Pragma("unroll") for (int n = 0; n < 2; ++n) { if constexpr (FP8) dst##8[n] = PG8_LD32(lds + PG8_SB(b, h) + boff + n * 2048); else { _Pragma("unroll") for (int k = 0; k < 2; ++k) dst[n][k] = *(const PG8_LAS bf16x8*)(lds + PG8_SB(b, h) + boff + n * 2048 + k * 1024); } } } while (0)
; #define PG8_WAIT_V(n) asm volatile("s_waitcnt vmcnt(" #n ")" ::: "memory")
; #define PG8_WAIT_L(n) asm volatile("s_waitcnt lgkmcnt(" #n ")" ::: "memory")
; #define PG8_BAR __builtin_amdgcn_s_barrier()
; #define PG8_SCHED __builtin_amdgcn_sched_barrier(0)
; template <class Epi, class Sched, bool ALIGN_EPI = false, bool SP2 = false, bool FP8 = false>
; __device__ __forceinline__ void gemm_phase(PG8_LAS unsigned char* lds, const Gemm g, const Sched& S, const Epi& E, int wave_id) {
;     ...
;             PG8_LDB(B0, 0, 0); PG8_LDB(B1, 0, 1); PG8_SCHED; PG8_LDA(At, 0, 0); PG8_STAGE(PG8_SA(1, 1), a1 + hstep, voffA);
;             PG8_WAIT_V(8); PG8_WAIT_L(0); PG8_BAR; PG8_MMA(0, 0, At, B0); PG8_MMA(0, 1, At, B1); PG8_BAR; PG8_SCHED;
;             PG8_LDA(At, 0, 1); PG8_STAGE(PG8_SB(0, 0), b2, voffB); PG8_STAGE(PG8_SB(0, 1), b2 + hstep, voffB); PG8_STAGE(PG8_SA(0, 0), a2, voffA);
;             PG8_WAIT_V(8); PG8_WAIT_L(0); PG8_BAR; PG8_MMA(1, 0, At, B0); PG8_MMA(1, 1, At, B1); PG8_BAR; PG8_SCHED;
;             PG8_LDB(B0, 1, 0); PG8_LDB(B1, 1, 1); PG8_SCHED; PG8_LDA(At, 1, 0); PG8_STAGE(PG8_SA(0, 1), a2 + hstep, voffA);
;             PG8_WAIT_V(8); PG8_WAIT_L(0); PG8_BAR; PG8_MMA(0, 0, At, B0); PG8_MMA(0, 1, At, B1); PG8_BAR; PG8_SCHED;
.LBB0_419:
	ds_read_b128 v[16:19], v187
	ds_read_b128 v[20:23], v187 offset:1024
	ds_read_b128 v[24:27], v187 offset:2048
	ds_read_b128 v[28:31], v187 offset:3072
	ds_read_b128 v[0:3], v188
	ds_read_b128 v[4:7], v188 offset:1024
	ds_read_b128 v[8:11], v188 offset:2048
	ds_read_b128 v[12:15], v188 offset:3072
	s_add_u32 s34, s30, 0xfffc0080
	s_addc_u32 s35, s31, -1
	s_cmp_eq_u32 s74, 12
	s_cselect_b32 s37, s23, s35
	s_cselect_b32 s36, s66, s34
	s_cselect_b32 s35, s21, s71
	s_cselect_b32 s34, s67, s69
	v_lshl_add_u64 v[216:217], s[30:31], 0, v[168:169]
	s_add_i32 m0, s29, 0xc000
	ds_read_b128 v[176:179], v189
	ds_read_b128 v[180:183], v189 offset:1024
	ds_read_b128 v[192:195], v189 offset:2048
	ds_read_b128 v[196:199], v189 offset:3072
	ds_read_b128 v[200:203], v189 offset:4096
	ds_read_b128 v[204:207], v189 offset:5120
	ds_read_b128 v[208:211], v189 offset:6144
	ds_read_b128 v[212:215], v189 offset:7168
	global_load_lds_dwordx4 v[216:217], off
	v_lshl_add_u64 v[216:217], s[30:31], 0, v[170:171]
	s_add_i32 m0, s29, 0xe000
	s_nop 0
	global_load_lds_dwordx4 v[216:217], off
	s_waitcnt vmcnt(8)
	s_waitcnt lgkmcnt(0)
	s_barrier
	s_setprio 1
	s_waitcnt lgkmcnt(0)
	v_mfma_f32_16x16x128_f8f6f4 v[156:159], v[16:23], v[176:183], v[156:159]
	v_mfma_f32_16x16x128_f8f6f4 v[152:155], v[24:31], v[176:183], v[152:155]
	v_mfma_f32_16x16x128_f8f6f4 v[148:151], v[16:23], v[192:199], v[148:151]
	v_mfma_f32_16x16x128_f8f6f4 v[136:139], v[24:31], v[192:199], v[136:139]
	v_mfma_f32_16x16x128_f8f6f4 v[124:127], v[16:23], v[200:207], v[124:127]
	v_mfma_f32_16x16x128_f8f6f4 v[120:123], v[24:31], v[200:207], v[120:123]
	v_mfma_f32_16x16x128_f8f6f4 v[108:111], v[16:23], v[208:215], v[108:111]
	v_mfma_f32_16x16x128_f8f6f4 v[104:107], v[24:31], v[208:215], v[104:107]
	s_setprio 0
	s_setprio 1
	v_mfma_f32_16x16x128_f8f6f4 v[144:147], v[0:7], v[176:183], v[144:147]
	v_mfma_f32_16x16x128_f8f6f4 v[140:143], v[8:15], v[176:183], v[140:143]
	v_mfma_f32_16x16x128_f8f6f4 v[132:135], v[0:7], v[192:199], v[132:135]
	v_mfma_f32_16x16x128_f8f6f4 v[128:131], v[8:15], v[192:199], v[128:131]
	v_mfma_f32_16x16x128_f8f6f4 v[116:119], v[0:7], v[200:207], v[116:119]
	v_mfma_f32_16x16x128_f8f6f4 v[112:115], v[8:15], v[200:207], v[112:115]
	v_mfma_f32_16x16x128_f8f6f4 v[100:103], v[0:7], v[208:215], v[100:103]
	v_mfma_f32_16x16x128_f8f6f4 v[96:99], v[8:15], v[208:215], v[96:99]
	s_setprio 0
	s_barrier
	s_add_i32 s75, s59, s44
	v_lshl_add_u64 v[176:177], s[34:35], 0, v[162:163]
	s_mov_b32 m0, s75
	ds_read_b128 v[192:195], v189 offset:16384
	ds_read_b128 v[196:199], v189 offset:17408
	ds_read_b128 v[200:203], v189 offset:18432
	ds_read_b128 v[204:207], v189 offset:19456
	ds_read_b128 v[208:211], v189 offset:20480
	ds_read_b128 v[212:215], v189 offset:21504
	ds_read_b128 v[216:219], v189 offset:22528
	ds_read_b128 v[220:223], v189 offset:23552
	global_load_lds_dwordx4 v[176:177], off
	s_add_i32 m0, s75, 0x2000
	s_add_u32 s78, s34, 0x40000
	v_lshl_add_u64 v[178:179], s[34:35], 0, v[166:167]
	s_addc_u32 s79, s35, 0
	s_add_i32 s75, s60, s44
	global_load_lds_dwordx4 v[178:179], off
	v_lshl_add_u64 v[180:181], s[78:79], 0, v[162:163]
	s_mov_b32 m0, s75
	v_lshl_add_u64 v[182:183], s[36:37], 0, v[164:165]
	global_load_lds_dwordx4 v[180:181], off
	v_lshl_add_u64 v[180:181], s[78:79], 0, v[166:167]
	s_add_i32 m0, s75, 0x2000
	s_nop 0
	global_load_lds_dwordx4 v[180:181], off
	v_lshl_add_u64 v[180:181], s[36:37], 0, v[160:161]
	s_mov_b32 m0, s29
	s_nop 0
	global_load_lds_dwordx4 v[180:181], off
	s_mov_b32 m0, s45
	s_nop 0
	global_load_lds_dwordx4 v[182:183], off
	s_waitcnt vmcnt(8)
	s_waitcnt lgkmcnt(0)
	s_barrier
	s_setprio 1
	s_waitcnt lgkmcnt(0)
	v_mfma_f32_16x16x128_f8f6f4 v[92:95], v[16:23], v[192:199], v[92:95]
	v_mfma_f32_16x16x128_f8f6f4 v[88:91], v[24:31], v[192:199], v[88:91]
	v_mfma_f32_16x16x128_f8f6f4 v[76:79], v[16:23], v[200:207], v[76:79]
	v_mfma_f32_16x16x128_f8f6f4 v[72:75], v[24:31], v[200:207], v[72:75]
	v_mfma_f32_16x16x128_f8f6f4 v[60:63], v[16:23], v[208:215], v[60:63]
	v_mfma_f32_16x16x128_f8f6f4 v[56:59], v[24:31], v[208:215], v[56:59]
	v_mfma_f32_16x16x128_f8f6f4 v[44:47], v[16:23], v[216:223], v[44:47]
	v_mfma_f32_16x16x128_f8f6f4 v[40:43], v[24:31], v[216:223], v[40:43]
	s_setprio 0
	s_setprio 1
	v_mfma_f32_16x16x128_f8f6f4 v[84:87], v[0:7], v[192:199], v[84:87]
	v_mfma_f32_16x16x128_f8f6f4 v[80:83], v[8:15], v[192:199], v[80:83]
	v_mfma_f32_16x16x128_f8f6f4 v[68:71], v[0:7], v[200:207], v[68:71]
	v_mfma_f32_16x16x128_f8f6f4 v[64:67], v[8:15], v[200:207], v[64:67]
	v_mfma_f32_16x16x128_f8f6f4 v[52:55], v[0:7], v[208:215], v[52:55]
	v_mfma_f32_16x16x128_f8f6f4 v[48:51], v[8:15], v[208:215], v[48:51]
	v_mfma_f32_16x16x128_f8f6f4 v[36:39], v[0:7], v[216:223], v[36:39]
	v_mfma_f32_16x16x128_f8f6f4 v[32:35], v[8:15], v[216:223], v[32:35]
	s_setprio 0
	s_barrier
	s_add_i32 s75, 0, 0x18000
	s_add_i32 s78, 0, 0x1c000
	v_add_u32_e32 v12, s75, v185
	v_add_u32_e32 v28, s78, v185
	ds_read_b128 v[0:3], v12
	ds_read_b128 v[4:7], v12 offset:1024
	ds_read_b128 v[8:11], v12 offset:2048
	ds_read_b128 v[12:15], v12 offset:3072
	ds_read_b128 v[16:19], v28
	ds_read_b128 v[20:23], v28 offset:1024
	ds_read_b128 v[24:27], v28 offset:2048
	ds_read_b128 v[28:31], v28 offset:3072
	s_add_u32 s36, s36, 0x40000
	s_addc_u32 s37, s37, 0
	s_mov_b32 m0, s52
	v_lshl_add_u64 v[224:225], s[36:37], 0, v[160:161]
	ds_read_b128 v[192:195], v189 offset:32768
	ds_read_b128 v[196:199], v189 offset:33792
	ds_read_b128 v[200:203], v189 offset:34816
	ds_read_b128 v[204:207], v189 offset:35840
	ds_read_b128 v[208:211], v189 offset:36864
	ds_read_b128 v[212:215], v189 offset:37888
	ds_read_b128 v[216:219], v189 offset:38912
	ds_read_b128 v[220:223], v189 offset:39936
	global_load_lds_dwordx4 v[224:225], off
	v_lshl_add_u64 v[224:225], s[36:37], 0, v[164:165]
	s_mov_b32 m0, s53
	s_nop 0
	global_load_lds_dwordx4 v[224:225], off
	s_waitcnt vmcnt(8)
	s_waitcnt lgkmcnt(0)
	s_barrier
; #define PG8_STAGE(bufoff, gbase, voff) do { _Pragma("unroll") for (int _i = 0; _i < 2; ++_i) \
;         __builtin_amdgcn_global_load_lds((const unsigned*)((const char*)(gbase) + (voff)[_i]), (PG8_LAS unsigned*)(lds + (bufoff) + ldsw + _i * 8192), 16, 0, 0); } while (0)
; #define PG8_LDA(dst, b, h) do { _Pragma("unroll") for (int m = 0; m < 4; ++m) { if constexpr (FP8) dst##8[m] = PG8_LD32(lds + PG8_SA(b, h) + aoff + m * 2048); else { _Pragma("unroll") for (int k = 0; k < 2; ++k) dst[m][k] = *(const PG8_LAS bf16x8*)(lds + PG8_SA(b, h) + aoff + m * 2048 + k * 1024); } } } while (0)
; #define PG8_WAIT_V(n) asm volatile("s_waitcnt vmcnt(" #n ")" ::: "memory")
; #define PG8_WAIT_L(n) asm volatile("s_waitcnt lgkmcnt(" #n ")" ::: "memory")
; #define PG8_BAR __builtin_amdgcn_s_barrier()
; #define PG8_SCHED __builtin_amdgcn_sched_barrier(0)
; template <class Epi, class Sched, bool ALIGN_EPI = false, bool SP2 = false, bool FP8 = false>
; __device__ __forceinline__ void gemm_phase(PG8_LAS unsigned char* lds, const Gemm g, const Sched& S, const Epi& E, int wave_id) {
;     ...
;             PG8_WAIT_V(8); PG8_WAIT_L(0); PG8_BAR; PG8_MMA(0, 0, At, B0); PG8_MMA(0, 1, At, B1); PG8_BAR; PG8_SCHED;
;             PG8_LDA(At, 1, 1); PG8_STAGE(PG8_SB(1, 0), b3, voffB); PG8_STAGE(PG8_SB(1, 1), b3 + hstep, voffB); PG8_STAGE(PG8_SA(1, 0), a3, voffA);
;             PG8_WAIT_V(8); PG8_WAIT_L(0); PG8_BAR; PG8_MMA(1, 0, At, B0); PG8_MMA(1, 1, At, B1); PG8_BAR; PG8_SCHED;
;     ...
;         if constexpr (FP8) asm volatile("s_nop 15\n\ts_nop 15" ::: "memory");
;     __device__ __forceinline__ void operator()(const f32x4 (&acc)[2][2][4][2], const Unit& u, int wr, int wc, int fr, int fq) const {
;         const int row0 = u.pm * BM + wr * 64 + fr, col0 = u.pn * BM + wc * 32 + 8 * fq;
;         float rs[2][4];
; #pragma unroll
;         for (int ai = 0; ai < 2; ++ai)
; #pragma unroll
;             for (int m = 0; m < 4; ++m) rs[ai][m] = __hip_atomic_load(ss + row0 + ai * HALF + m * 16, __ATOMIC_RELAXED, __HIP_MEMORY_SCOPE_AGENT);
;         asm volatile("" ::: "memory");
	s_setprio 1
	s_waitcnt lgkmcnt(0)
	v_mfma_f32_16x16x128_f8f6f4 v[156:159], v[0:7], v[192:199], v[156:159]
	v_mfma_f32_16x16x128_f8f6f4 v[152:155], v[8:15], v[192:199], v[152:155]
	v_mfma_f32_16x16x128_f8f6f4 v[148:151], v[0:7], v[200:207], v[148:151]
	v_mfma_f32_16x16x128_f8f6f4 v[136:139], v[8:15], v[200:207], v[136:139]
	v_mfma_f32_16x16x128_f8f6f4 v[124:127], v[0:7], v[208:215], v[124:127]
	v_mfma_f32_16x16x128_f8f6f4 v[120:123], v[8:15], v[208:215], v[120:123]
	v_mfma_f32_16x16x128_f8f6f4 v[108:111], v[0:7], v[216:223], v[108:111]
	v_mfma_f32_16x16x128_f8f6f4 v[104:107], v[8:15], v[216:223], v[104:107]
	s_setprio 0
	s_setprio 1
	v_mfma_f32_16x16x128_f8f6f4 v[144:147], v[16:23], v[192:199], v[144:147]
	v_mfma_f32_16x16x128_f8f6f4 v[140:143], v[24:31], v[192:199], v[140:143]
	v_mfma_f32_16x16x128_f8f6f4 v[132:135], v[16:23], v[200:207], v[132:135]
	v_mfma_f32_16x16x128_f8f6f4 v[128:131], v[24:31], v[200:207], v[128:131]
	v_mfma_f32_16x16x128_f8f6f4 v[116:119], v[16:23], v[208:215], v[116:119]
	v_mfma_f32_16x16x128_f8f6f4 v[112:115], v[24:31], v[208:215], v[112:115]
	v_mfma_f32_16x16x128_f8f6f4 v[100:103], v[16:23], v[216:223], v[100:103]
	v_mfma_f32_16x16x128_f8f6f4 v[96:99], v[24:31], v[216:223], v[96:99]
	s_setprio 0
	s_barrier
	s_add_i32 s36, s75, s44
	v_lshl_add_u64 v[176:177], v[176:177], 0, s[10:11]
	s_mov_b32 m0, s36
	ds_read_b128 v[192:195], v189 offset:49152
	ds_read_b128 v[196:199], v189 offset:50176
	ds_read_b128 v[200:203], v189 offset:51200
	ds_read_b128 v[204:207], v189 offset:52224
	ds_read_b128 v[208:211], v189 offset:53248
	ds_read_b128 v[212:215], v189 offset:54272
	ds_read_b128 v[216:219], v189 offset:55296
	ds_read_b128 v[220:223], v189 offset:56320
	global_load_lds_dwordx4 v[176:177], off
	s_add_i32 m0, s36, 0x2000
	s_add_u32 s34, s34, 0x40080
	v_lshl_add_u64 v[176:177], v[178:179], 0, s[10:11]
	s_addc_u32 s35, s35, 0
	s_add_i32 s36, s78, s44
	global_load_lds_dwordx4 v[176:177], off
	v_lshl_add_u64 v[176:177], s[34:35], 0, v[162:163]
	s_mov_b32 m0, s36
	s_nop 0
	global_load_lds_dwordx4 v[176:177], off
	v_lshl_add_u64 v[176:177], s[34:35], 0, v[166:167]
	s_add_i32 m0, s36, 0x2000
	s_nop 0
	global_load_lds_dwordx4 v[176:177], off
	v_lshl_add_u64 v[176:177], v[180:181], 0, s[10:11]
	s_mov_b32 m0, s55
	s_nop 0
	global_load_lds_dwordx4 v[176:177], off
	v_lshl_add_u64 v[176:177], v[182:183], 0, s[10:11]
	s_mov_b32 m0, s56
	s_nop 0
	global_load_lds_dwordx4 v[176:177], off
	s_waitcnt vmcnt(8)
	s_waitcnt lgkmcnt(0)
	s_barrier
	s_setprio 1
	s_waitcnt lgkmcnt(0)
	v_mfma_f32_16x16x128_f8f6f4 v[92:95], v[0:7], v[192:199], v[92:95]
	v_mfma_f32_16x16x128_f8f6f4 v[88:91], v[8:15], v[192:199], v[88:91]
	v_mfma_f32_16x16x128_f8f6f4 v[76:79], v[0:7], v[200:207], v[76:79]
	v_mfma_f32_16x16x128_f8f6f4 v[72:75], v[8:15], v[200:207], v[72:75]
	v_mfma_f32_16x16x128_f8f6f4 v[60:63], v[0:7], v[208:215], v[60:63]
	v_mfma_f32_16x16x128_f8f6f4 v[56:59], v[8:15], v[208:215], v[56:59]
	v_mfma_f32_16x16x128_f8f6f4 v[44:47], v[0:7], v[216:223], v[44:47]
	v_mfma_f32_16x16x128_f8f6f4 v[40:43], v[8:15], v[216:223], v[40:43]
	s_setprio 0
	s_setprio 1
	v_mfma_f32_16x16x128_f8f6f4 v[84:87], v[16:23], v[192:199], v[84:87]
	v_mfma_f32_16x16x128_f8f6f4 v[80:83], v[24:31], v[192:199], v[80:83]
	v_mfma_f32_16x16x128_f8f6f4 v[68:71], v[16:23], v[200:207], v[68:71]
	v_mfma_f32_16x16x128_f8f6f4 v[64:67], v[24:31], v[200:207], v[64:67]
	v_mfma_f32_16x16x128_f8f6f4 v[52:55], v[16:23], v[208:215], v[52:55]
	v_mfma_f32_16x16x128_f8f6f4 v[48:51], v[24:31], v[208:215], v[48:51]
	v_mfma_f32_16x16x128_f8f6f4 v[36:39], v[16:23], v[216:223], v[36:39]
	v_mfma_f32_16x16x128_f8f6f4 v[32:35], v[24:31], v[216:223], v[32:35]
	s_setprio 0
	s_barrier
	s_add_i32 s74, s74, 2
	s_add_u32 s30, s30, 0x100
	s_addc_u32 s31, s31, 0
	s_add_u32 s69, s69, 0x100
	s_addc_u32 s71, s71, 0
	s_cmp_gt_u32 s74, 13
	s_cbranch_scc0 .LBB0_419
	v_lshl_add_u32 v4, s28, 8, v184
	v_ashrrev_i32_e32 v5, 31, v4
	s_nop 15
	s_nop 15
	v_lshl_add_u64 v[0:1], v[4:5], 2, s[8:9]
	v_lshlrev_b64 v[14:15], 13, v[4:5]
	v_lshl_add_u64 v[0:1], s[40:41], 0, v[14:15]
	v_mov_b32_e32 v8, 0
	v_mov_b32_e32 v9, 0
	v_mov_b32_e32 v10, 0
	v_mov_b32_e32 v11, 0
	v_lshl_or_b32 v2, s65, 8, v186
	v_ashrrev_i32_e32 v3, 31, v2
	v_lshl_add_u64 v[0:1], v[0:1], 0, v[2:3]
	v_or_b32_e32 v12, 16, v4
	v_ashrrev_i32_e32 v13, 31, v12
	v_lshlrev_b64 v[12:13], 13, v[12:13]
	s_mov_b32 s65, s20
	s_mov_b32 s28, s22
	s_mov_b64 s[34:35], s[26:27]
	s_mov_b64 s[30:31], s[24:25]
	s_waitcnt vmcnt(8)
;     __device__ __forceinline__ void operator()(const f32x4 (&acc)[2][2][4][2], const Unit& u, int wr, int wc, int fr, int fq) const {
;     ...
;         for (int ai = 0; ai < 2; ++ai)
; #pragma unroll
;             for (int m = 0; m < 4; ++m) {
;                 const int row = row0 + ai * HALF + m * 16;
;                 const float rstd = __builtin_amdgcn_rsqf(rs[ai][m] * (1.f / DM) + EPS) * (1.f / W1_SCALE);
; #pragma unroll
;                 for (int bj = 0; bj < 2; ++bj) {
;                     f32x4 v0 = acc[ai][bj][m][0] * rstd, v1 = acc[ai][bj][m][1] * rstd;
; #pragma unroll
;                     for (int e = 0; e < 4; ++e) { const float a = fmaxf(v0[e], 0.f), b = fmaxf(v1[e], 0.f); v0[e] = fminf(a * a, 448.f); v1[e] = fminf(b * b, 448.f); }
;                     int w0 = __builtin_amdgcn_cvt_pk_fp8_f32(v0[0], v0[1], 0, false); w0 = __builtin_amdgcn_cvt_pk_fp8_f32(v0[2], v0[3], w0, true);
;                     int w1 = __builtin_amdgcn_cvt_pk_fp8_f32(v1[0], v1[1], 0, false); w1 = __builtin_amdgcn_cvt_pk_fp8_f32(v1[2], v1[3], w1, true);
;                     *(v2u*)(O + (size_t)row * FF + col0 + bj * HALF) = (v2u){(unsigned)w0, (unsigned)w1};
;                 }
	v_mov_b32_e32 v7, v226
	v_mov_b32_e32 v16, v227
	v_mov_b32_e32 v176, v228
	v_mov_b32_e32 v177, v229
	v_mov_b32_e32 v178, v230
	v_mov_b32_e32 v179, v231
	v_mov_b32_e32 v6, v232
	v_mov_b32_e32 v5, v233
	v_fmamk_f32 v7, v7, 0x3a000000, v190
	v_fmamk_f32 v14, v16, 0x3a000000, v190
	v_rsq_f32_e32 v7, v7
	v_rsq_f32_e32 v15, v14
	v_mul_f32_e32 v14, 0x3d000000, v7
	v_mul_f32_e32 v16, 0x3d000000, v15
	v_pk_mul_f32 v[20:21], v[156:157], v[14:15] op_sel_hi:[1,0]
	v_pk_mul_f32 v[24:25], v[152:153], v[14:15] op_sel_hi:[1,0]
	v_pk_mul_f32 v[18:19], v[158:159], v[14:15] op_sel_hi:[1,0]
	v_pk_mul_f32 v[22:23], v[154:155], v[14:15] op_sel_hi:[1,0]
	v_pk_mul_f32 v[26:27], v[146:147], v[14:15] op_sel_hi:[1,0]
	v_pk_mul_f32 v[28:29], v[144:145], v[14:15] op_sel_hi:[1,0]
	v_pk_mul_f32 v[30:31], v[142:143], v[14:15] op_sel_hi:[1,0]
	v_pk_mul_f32 v[14:15], v[140:141], v[14:15] op_sel_hi:[1,0]
	v_pk_mul_f32 v[140:141], v[150:151], v[16:17] op_sel_hi:[1,0]
	v_pk_mul_f32 v[142:143], v[148:149], v[16:17] op_sel_hi:[1,0]
	v_pk_mul_f32 v[138:139], v[138:139], v[16:17] op_sel_hi:[1,0]
	v_max_f32_e32 v7, 0, v20
	v_max_f32_e32 v17, 0, v24
	v_max_f32_e32 v20, 0, v21
	v_max_f32_e32 v21, 0, v25
	v_max_f32_e32 v24, 0, v28
	v_max_f32_e32 v14, 0, v14
	v_max_f32_e32 v25, 0, v29
	v_max_f32_e32 v15, 0, v15
	v_mul_f32_e32 v7, v7, v7
	v_mul_f32_e32 v17, v17, v17
	v_mul_f32_e32 v20, v20, v20
	v_mul_f32_e32 v21, v21, v21
	v_mul_f32_e32 v24, v24, v24
	v_mul_f32_e32 v14, v14, v14
	v_mul_f32_e32 v25, v25, v25
	v_mul_f32_e32 v15, v15, v15
	v_min_f32_e32 v7, 0x43e00000, v7
	v_min_f32_e32 v17, 0x43e00000, v17
	v_min_f32_e32 v20, 0x43e00000, v20
	v_min_f32_e32 v21, 0x43e00000, v21
	v_min_f32_e32 v24, 0x43e00000, v24
	v_min_f32_e32 v14, 0x43e00000, v14
	v_min_f32_e32 v25, 0x43e00000, v25
	v_min_f32_e32 v15, 0x43e00000, v15
	v_cvt_pk_fp8_f32 v8, v7, v20
	v_cvt_pk_fp8_f32 v9, v17, v21
	v_max_f32_e32 v18, 0, v18
	v_max_f32_e32 v22, 0, v22
	v_max_f32_e32 v19, 0, v19
	v_max_f32_e32 v23, 0, v23
	v_cvt_pk_fp8_f32 v10, v24, v25
	v_cvt_pk_fp8_f32 v11, v14, v15
	v_max_f32_e32 v26, 0, v26
	v_max_f32_e32 v28, 0, v30
	v_max_f32_e32 v27, 0, v27
	v_max_f32_e32 v29, 0, v31
	v_mul_f32_e32 v18, v18, v18
	v_mul_f32_e32 v22, v22, v22
	v_mul_f32_e32 v19, v19, v19
	v_mul_f32_e32 v23, v23, v23
	v_mul_f32_e32 v26, v26, v26
	v_mul_f32_e32 v28, v28, v28
	v_mul_f32_e32 v27, v27, v27
	v_mul_f32_e32 v29, v29, v29
	v_min_f32_e32 v18, 0x43e00000, v18
	v_min_f32_e32 v22, 0x43e00000, v22
	v_min_f32_e32 v19, 0x43e00000, v19
	v_min_f32_e32 v23, 0x43e00000, v23
	v_min_f32_e32 v26, 0x43e00000, v26
	v_min_f32_e32 v28, 0x43e00000, v28
	v_min_f32_e32 v27, 0x43e00000, v27
	v_min_f32_e32 v29, 0x43e00000, v29
	v_cvt_pk_fp8_f32 v8, v18, v19 op_sel:[0,0,1]
	v_cvt_pk_fp8_f32 v9, v22, v23 op_sel:[0,0,1]
	v_cvt_pk_fp8_f32 v10, v26, v27 op_sel:[0,0,1]
	v_cvt_pk_fp8_f32 v11, v28, v29 op_sel:[0,0,1]
	v_pk_mul_f32 v[14:15], v[136:137], v[16:17] op_sel_hi:[1,0]
	global_store_dwordx2 v[0:1], v[8:9], off
	global_store_dwordx2 v[0:1], v[10:11], off offset:128
	v_max_f32_e32 v8, 0, v14
	v_mul_f32_e32 v8, v8, v8
	v_min_f32_e32 v10, 0x43e00000, v8
	v_max_f32_e32 v8, 0, v143
	v_max_f32_e32 v9, 0, v15
	v_mul_f32_e32 v8, v8, v8
	v_min_f32_e32 v11, 0x43e00000, v8
	v_mul_f32_e32 v8, v9, v9
	v_min_f32_e32 v14, 0x43e00000, v8
	v_max_f32_e32 v8, 0, v140
	v_max_f32_e32 v9, 0, v138
	v_mul_f32_e32 v8, v8, v8
	v_min_f32_e32 v15, 0x43e00000, v8
	v_mul_f32_e32 v8, v9, v9
	v_max_f32_e32 v7, 0, v142
	v_min_f32_e32 v17, 0x43e00000, v8
	v_max_f32_e32 v8, 0, v141
	v_mul_f32_e32 v7, v7, v7
	v_mul_f32_e32 v8, v8, v8
	v_min_f32_e32 v7, 0x43e00000, v7
	v_min_f32_e32 v19, 0x43e00000, v8
	v_mov_b32_e32 v8, 0
	v_mov_b32_e32 v9, 0
	v_cvt_pk_fp8_f32 v8, v7, v11
	v_cvt_pk_fp8_f32 v9, v10, v14
	v_max_f32_e32 v18, 0, v139
	v_mul_f32_e32 v7, v18, v18
	v_min_f32_e32 v7, 0x43e00000, v7
	v_lshl_add_u64 v[10:11], s[40:41], 0, v[12:13]
	v_pk_mul_f32 v[12:13], v[134:135], v[16:17] op_sel_hi:[1,0]
	v_cvt_pk_fp8_f32 v8, v15, v19 op_sel:[0,0,1]
	v_cvt_pk_fp8_f32 v9, v17, v7 op_sel:[0,0,1]
	v_pk_mul_f32 v[14:15], v[132:133], v[16:17] op_sel_hi:[1,0]
	v_pk_mul_f32 v[18:19], v[130:131], v[16:17] op_sel_hi:[1,0]
	v_pk_mul_f32 v[16:17], v[128:129], v[16:17] op_sel_hi:[1,0]
	v_max_f32_e32 v12, 0, v12
	v_max_f32_e32 v7, 0, v14
	v_max_f32_e32 v14, 0, v16
	v_max_f32_e32 v16, 0, v17
	v_max_f32_e32 v17, 0, v18
	v_mul_f32_e32 v12, v12, v12
	v_mul_f32_e32 v14, v14, v14
	v_mul_f32_e32 v16, v16, v16
	v_min_f32_e32 v18, 0x43e00000, v12
	v_mul_f32_e32 v12, v17, v17
	v_min_f32_e32 v14, 0x43e00000, v14
	v_max_f32_e32 v15, 0, v15
	v_min_f32_e32 v16, 0x43e00000, v16
	v_min_f32_e32 v17, 0x43e00000, v12
	v_max_f32_e32 v12, 0, v13
	v_mov_b32_e32 v13, 0
	v_mul_f32_e32 v7, v7, v7
	v_mul_f32_e32 v15, v15, v15
	v_mul_f32_e32 v12, v12, v12
	v_cvt_pk_fp8_f32 v13, v14, v16
	v_min_f32_e32 v7, 0x43e00000, v7
	v_min_f32_e32 v15, 0x43e00000, v15
	v_max_f32_e32 v19, 0, v19
	v_min_f32_e32 v20, 0x43e00000, v12
	v_mov_b32_e32 v12, 0
	v_cvt_pk_fp8_f32 v12, v7, v15
	v_mul_f32_e32 v7, v19, v19
	v_min_f32_e32 v7, 0x43e00000, v7
	v_cvt_pk_fp8_f32 v13, v17, v7 op_sel:[0,0,1]
	v_fmamk_f32 v7, v176, 0x3a000000, v190
	v_rsq_f32_e32 v7, v7
	v_cvt_pk_fp8_f32 v12, v18, v20 op_sel:[0,0,1]
	v_lshl_add_u64 v[10:11], v[10:11], 0, v[2:3]
	global_store_dwordx2 v[10:11], v[8:9], off
	global_store_dwordx2 v[10:11], v[12:13], off offset:128
	v_mul_f32_e32 v10, 0x3d000000, v7
	v_pk_mul_f32 v[12:13], v[126:127], v[10:11] op_sel_hi:[1,0]
	v_pk_mul_f32 v[16:17], v[122:123], v[10:11] op_sel_hi:[1,0]
	v_max_f32_e32 v12, 0, v12
	v_pk_mul_f32 v[18:19], v[120:121], v[10:11] op_sel_hi:[1,0]
	v_max_f32_e32 v16, 0, v16
	v_mul_f32_e32 v12, v12, v12
;     __device__ __forceinline__ void operator()(const f32x4 (&acc)[2][2][4][2], const Unit& u, int wr, int wc, int fr, int fq) const {
;     ...
;         for (int ai = 0; ai < 2; ++ai)
; #pragma unroll
;             for (int m = 0; m < 4; ++m) {
;                 const int row = row0 + ai * HALF + m * 16;
;                 const float rstd = __builtin_amdgcn_rsqf(rs[ai][m] * (1.f / DM) + EPS) * (1.f / W1_SCALE);
; #pragma unroll
;                 for (int bj = 0; bj < 2; ++bj) {
;                     f32x4 v0 = acc[ai][bj][m][0] * rstd, v1 = acc[ai][bj][m][1] * rstd;
; #pragma unroll
;                     for (int e = 0; e < 4; ++e) { const float a = fmaxf(v0[e], 0.f), b = fmaxf(v1[e], 0.f); v0[e] = fminf(a * a, 448.f); v1[e] = fminf(b * b, 448.f); }
;                     int w0 = __builtin_amdgcn_cvt_pk_fp8_f32(v0[0], v0[1], 0, false); w0 = __builtin_amdgcn_cvt_pk_fp8_f32(v0[2], v0[3], w0, true);
;                     int w1 = __builtin_amdgcn_cvt_pk_fp8_f32(v1[0], v1[1], 0, false); w1 = __builtin_amdgcn_cvt_pk_fp8_f32(v1[2], v1[3], w1, true);
;                     *(v2u*)(O + (size_t)row * FF + col0 + bj * HALF) = (v2u){(unsigned)w0, (unsigned)w1};
;                 }
	v_pk_mul_f32 v[14:15], v[124:125], v[10:11] op_sel_hi:[1,0]
	v_max_f32_e32 v11, 0, v18
	v_min_f32_e32 v18, 0x43e00000, v12
	v_mul_f32_e32 v12, v16, v16
	v_max_f32_e32 v7, 0, v14
	v_max_f32_e32 v14, 0, v15
	v_max_f32_e32 v15, 0, v19
	v_min_f32_e32 v16, 0x43e00000, v12
	v_max_f32_e32 v12, 0, v13
	v_mul_f32_e32 v7, v7, v7
	v_mul_f32_e32 v11, v11, v11
	v_mul_f32_e32 v14, v14, v14
	v_mul_f32_e32 v15, v15, v15
	v_mul_f32_e32 v12, v12, v12
	v_min_f32_e32 v7, 0x43e00000, v7
	v_min_f32_e32 v11, 0x43e00000, v11
	v_min_f32_e32 v14, 0x43e00000, v14
	v_min_f32_e32 v15, 0x43e00000, v15
	v_min_f32_e32 v19, 0x43e00000, v12
	v_mov_b32_e32 v12, 0
	v_mov_b32_e32 v13, 0
	v_cvt_pk_fp8_f32 v12, v7, v14
	v_cvt_pk_fp8_f32 v13, v11, v15
	v_max_f32_e32 v17, 0, v17
	v_mul_f32_e32 v7, v17, v17
	v_min_f32_e32 v7, 0x43e00000, v7
	v_cvt_pk_fp8_f32 v12, v18, v19 op_sel:[0,0,1]
	v_cvt_pk_fp8_f32 v13, v16, v7 op_sel:[0,0,1]
	v_pk_mul_f32 v[14:15], v[118:119], v[10:11] op_sel_hi:[1,0]
	v_pk_mul_f32 v[16:17], v[116:117], v[10:11] op_sel_hi:[1,0]
	v_pk_mul_f32 v[18:19], v[114:115], v[10:11] op_sel_hi:[1,0]
	v_pk_mul_f32 v[10:11], v[112:113], v[10:11] op_sel_hi:[1,0]
	v_max_f32_e32 v7, 0, v16
	v_max_f32_e32 v10, 0, v10
	v_mul_f32_e32 v10, v10, v10
	v_min_f32_e32 v16, 0x43e00000, v10
	v_max_f32_e32 v10, 0, v17
	v_max_f32_e32 v11, 0, v11
	v_mul_f32_e32 v10, v10, v10
	v_min_f32_e32 v17, 0x43e00000, v10
	v_mul_f32_e32 v10, v11, v11
	v_min_f32_e32 v20, 0x43e00000, v10
	v_max_f32_e32 v10, 0, v14
	v_max_f32_e32 v11, 0, v18
	v_mul_f32_e32 v10, v10, v10
	v_min_f32_e32 v14, 0x43e00000, v10
	v_mul_f32_e32 v10, v11, v11
	v_min_f32_e32 v18, 0x43e00000, v10
	v_max_f32_e32 v10, 0, v15
	v_mov_b32_e32 v11, 0
	v_mul_f32_e32 v7, v7, v7
	v_mul_f32_e32 v10, v10, v10
	v_cvt_pk_fp8_f32 v11, v16, v20
	v_min_f32_e32 v7, 0x43e00000, v7
	v_max_f32_e32 v15, 0, v19
	v_min_f32_e32 v19, 0x43e00000, v10
	v_mov_b32_e32 v10, 0
	v_cvt_pk_fp8_f32 v10, v7, v17
	v_mul_f32_e32 v7, v15, v15
	v_min_f32_e32 v7, 0x43e00000, v7
	v_or_b32_e32 v8, 32, v4
	v_cvt_pk_fp8_f32 v11, v18, v7 op_sel:[0,0,1]
	v_fmamk_f32 v7, v177, 0x3a000000, v190
	v_ashrrev_i32_e32 v9, 31, v8
	v_rsq_f32_e32 v7, v7
	v_lshlrev_b64 v[8:9], 13, v[8:9]
	v_cvt_pk_fp8_f32 v10, v14, v19 op_sel:[0,0,1]
	v_lshl_add_u64 v[8:9], s[40:41], 0, v[8:9]
	v_lshl_add_u64 v[8:9], v[8:9], 0, v[2:3]
	global_store_dwordx2 v[8:9], v[12:13], off
	global_store_dwordx2 v[8:9], v[10:11], off offset:128
	v_or_b32_e32 v8, 48, v4
	v_mul_f32_e32 v4, 0x3d000000, v7
	v_pk_mul_f32 v[10:11], v[110:111], v[4:5] op_sel_hi:[1,0]
	v_pk_mul_f32 v[14:15], v[106:107], v[4:5] op_sel_hi:[1,0]
	v_max_f32_e32 v10, 0, v10
	v_pk_mul_f32 v[12:13], v[108:109], v[4:5] op_sel_hi:[1,0]
	v_pk_mul_f32 v[16:17], v[104:105], v[4:5] op_sel_hi:[1,0]
	v_max_f32_e32 v14, 0, v14
	v_mul_f32_e32 v10, v10, v10
	v_max_f32_e32 v7, 0, v12
	v_max_f32_e32 v12, 0, v16
	v_max_f32_e32 v16, 0, v17
	v_min_f32_e32 v17, 0x43e00000, v10
	v_mul_f32_e32 v10, v14, v14
	v_max_f32_e32 v13, 0, v13
	v_min_f32_e32 v14, 0x43e00000, v10
	v_max_f32_e32 v10, 0, v11
	v_mul_f32_e32 v7, v7, v7
	v_mul_f32_e32 v12, v12, v12
	v_mul_f32_e32 v13, v13, v13
	v_mul_f32_e32 v16, v16, v16
	v_mul_f32_e32 v10, v10, v10
	v_min_f32_e32 v7, 0x43e00000, v7
	v_min_f32_e32 v12, 0x43e00000, v12
	v_min_f32_e32 v13, 0x43e00000, v13
	v_min_f32_e32 v16, 0x43e00000, v16
	v_min_f32_e32 v18, 0x43e00000, v10
	v_mov_b32_e32 v10, 0
	v_mov_b32_e32 v11, 0
	v_cvt_pk_fp8_f32 v10, v7, v13
	v_cvt_pk_fp8_f32 v11, v12, v16
	v_max_f32_e32 v15, 0, v15
	v_mul_f32_e32 v7, v15, v15
	v_min_f32_e32 v7, 0x43e00000, v7
	v_pk_mul_f32 v[12:13], v[102:103], v[4:5] op_sel_hi:[1,0]
	v_cvt_pk_fp8_f32 v10, v17, v18 op_sel:[0,0,1]
	v_cvt_pk_fp8_f32 v11, v14, v7 op_sel:[0,0,1]
	v_pk_mul_f32 v[14:15], v[100:101], v[4:5] op_sel_hi:[1,0]
	v_pk_mul_f32 v[16:17], v[98:99], v[4:5] op_sel_hi:[1,0]
	v_pk_mul_f32 v[18:19], v[96:97], v[4:5] op_sel_hi:[1,0]
	v_max_f32_e32 v12, 0, v12
	v_max_f32_e32 v4, 0, v14
	v_max_f32_e32 v7, 0, v18
	v_max_f32_e32 v14, 0, v15
	v_max_f32_e32 v15, 0, v19
	v_max_f32_e32 v16, 0, v16
	v_mul_f32_e32 v12, v12, v12
	v_mul_f32_e32 v7, v7, v7
	v_mul_f32_e32 v15, v15, v15
	v_min_f32_e32 v18, 0x43e00000, v12
	v_mul_f32_e32 v12, v16, v16
	v_min_f32_e32 v7, 0x43e00000, v7
	v_min_f32_e32 v15, 0x43e00000, v15
	v_min_f32_e32 v16, 0x43e00000, v12
	v_max_f32_e32 v12, 0, v13
	v_mov_b32_e32 v13, 0
	v_mul_f32_e32 v4, v4, v4
	v_mul_f32_e32 v14, v14, v14
	v_mul_f32_e32 v12, v12, v12
	v_cvt_pk_fp8_f32 v13, v7, v15
	v_min_f32_e32 v4, 0x43e00000, v4
	v_min_f32_e32 v14, 0x43e00000, v14
	v_max_f32_e32 v17, 0, v17
	v_min_f32_e32 v19, 0x43e00000, v12
	v_mov_b32_e32 v12, 0
	v_cvt_pk_fp8_f32 v12, v4, v14
	v_mul_f32_e32 v4, v17, v17
	v_min_f32_e32 v4, 0x43e00000, v4
	v_cvt_pk_fp8_f32 v13, v16, v4 op_sel:[0,0,1]
	v_fmamk_f32 v4, v178, 0x3a000000, v190
	v_ashrrev_i32_e32 v9, 31, v8
	v_rsq_f32_e32 v4, v4
	v_lshlrev_b64 v[8:9], 13, v[8:9]
	v_cvt_pk_fp8_f32 v12, v18, v19 op_sel:[0,0,1]
	v_lshl_add_u64 v[8:9], s[40:41], 0, v[8:9]
	v_lshl_add_u64 v[2:3], v[8:9], 0, v[2:3]
	global_store_dwordx2 v[2:3], v[10:11], off
	global_store_dwordx2 v[2:3], v[12:13], off offset:128
	v_mul_f32_e32 v2, 0x3d000000, v4
	v_pk_mul_f32 v[8:9], v[94:95], v[2:3] op_sel_hi:[1,0]
	v_pk_mul_f32 v[10:11], v[92:93], v[2:3] op_sel_hi:[1,0]
	v_pk_mul_f32 v[12:13], v[90:91], v[2:3] op_sel_hi:[1,0]
	v_max_f32_e32 v8, 0, v8
	v_max_f32_e32 v7, 0, v11
	v_max_f32_e32 v11, 0, v12
	v_mul_f32_e32 v8, v8, v8
	v_pk_mul_f32 v[14:15], v[88:89], v[2:3] op_sel_hi:[1,0]
	v_min_f32_e32 v12, 0x43e00000, v8
	v_mul_f32_e32 v8, v11, v11
	v_max_f32_e32 v3, 0, v10
	v_max_f32_e32 v4, 0, v14
	v_max_f32_e32 v10, 0, v15
	v_min_f32_e32 v11, 0x43e00000, v8
;     __device__ __forceinline__ void operator()(const f32x4 (&acc)[2][2][4][2], const Unit& u, int wr, int wc, int fr, int fq) const {
;     ...
;         for (int ai = 0; ai < 2; ++ai)
; #pragma unroll
;             for (int m = 0; m < 4; ++m) {
;                 const int row = row0 + ai * HALF + m * 16;
;                 const float rstd = __builtin_amdgcn_rsqf(rs[ai][m] * (1.f / DM) + EPS) * (1.f / W1_SCALE);
; #pragma unroll
;                 for (int bj = 0; bj < 2; ++bj) {
;                     f32x4 v0 = acc[ai][bj][m][0] * rstd, v1 = acc[ai][bj][m][1] * rstd;
; #pragma unroll
;                     for (int e = 0; e < 4; ++e) { const float a = fmaxf(v0[e], 0.f), b = fmaxf(v1[e], 0.f); v0[e] = fminf(a * a, 448.f); v1[e] = fminf(b * b, 448.f); }
;                     int w0 = __builtin_amdgcn_cvt_pk_fp8_f32(v0[0], v0[1], 0, false); w0 = __builtin_amdgcn_cvt_pk_fp8_f32(v0[2], v0[3], w0, true);
;                     int w1 = __builtin_amdgcn_cvt_pk_fp8_f32(v1[0], v1[1], 0, false); w1 = __builtin_amdgcn_cvt_pk_fp8_f32(v1[2], v1[3], w1, true);
;                     *(v2u*)(O + (size_t)row * FF + col0 + bj * HALF) = (v2u){(unsigned)w0, (unsigned)w1};
;                 }
	v_max_f32_e32 v8, 0, v9
	v_mul_f32_e32 v3, v3, v3
	v_mul_f32_e32 v4, v4, v4
	v_mul_f32_e32 v7, v7, v7
	v_mul_f32_e32 v10, v10, v10
	v_mul_f32_e32 v8, v8, v8
	v_min_f32_e32 v3, 0x43e00000, v3
	v_min_f32_e32 v4, 0x43e00000, v4
	v_min_f32_e32 v7, 0x43e00000, v7
	v_min_f32_e32 v10, 0x43e00000, v10
	v_min_f32_e32 v14, 0x43e00000, v8
	v_mov_b32_e32 v8, 0
	v_mov_b32_e32 v9, 0
	v_cvt_pk_fp8_f32 v8, v3, v7
	v_cvt_pk_fp8_f32 v9, v4, v10
	v_max_f32_e32 v13, 0, v13
	v_mul_f32_e32 v3, v13, v13
	v_min_f32_e32 v3, 0x43e00000, v3
	v_cvt_pk_fp8_f32 v8, v12, v14 op_sel:[0,0,1]
	v_cvt_pk_fp8_f32 v9, v11, v3 op_sel:[0,0,1]
	v_pk_mul_f32 v[12:13], v[86:87], v[2:3] op_sel_hi:[1,0]
	v_pk_mul_f32 v[14:15], v[84:85], v[2:3] op_sel_hi:[1,0]
	v_pk_mul_f32 v[16:17], v[82:83], v[2:3] op_sel_hi:[1,0]
	v_pk_mul_f32 v[2:3], v[80:81], v[2:3] op_sel_hi:[1,0]
	v_max_f32_e32 v4, 0, v14
	v_max_f32_e32 v2, 0, v2
	v_mul_f32_e32 v2, v2, v2
	v_min_f32_e32 v7, 0x43e00000, v2
	v_max_f32_e32 v2, 0, v15
	v_max_f32_e32 v3, 0, v3
	v_mul_f32_e32 v2, v2, v2
	v_min_f32_e32 v14, 0x43e00000, v2
	v_mul_f32_e32 v2, v3, v3
	v_min_f32_e32 v15, 0x43e00000, v2
	v_max_f32_e32 v2, 0, v12
	v_max_f32_e32 v3, 0, v16
	v_mul_f32_e32 v2, v2, v2
	v_min_f32_e32 v12, 0x43e00000, v2
	v_mul_f32_e32 v2, v3, v3
	v_min_f32_e32 v16, 0x43e00000, v2
	v_max_f32_e32 v2, 0, v13
	v_mov_b32_e32 v3, 0
	v_mul_f32_e32 v4, v4, v4
	v_mul_f32_e32 v2, v2, v2
	v_cvt_pk_fp8_f32 v3, v7, v15
	v_min_f32_e32 v4, 0x43e00000, v4
	v_max_f32_e32 v13, 0, v17
	v_min_f32_e32 v17, 0x43e00000, v2
	v_mov_b32_e32 v2, 0
	v_cvt_pk_fp8_f32 v2, v4, v14
	v_mul_f32_e32 v4, v13, v13
	v_min_f32_e32 v4, 0x43e00000, v4
	v_cvt_pk_fp8_f32 v3, v16, v4 op_sel:[0,0,1]
	v_fmamk_f32 v4, v179, 0x3a000000, v190
	v_rsq_f32_e32 v4, v4
	v_cvt_pk_fp8_f32 v2, v12, v17 op_sel:[0,0,1]
	v_add_co_u32_e32 v12, vcc, s61, v0
	v_lshl_add_u64 v[10:11], v[0:1], 0, s[12:13]
	s_nop 0
	v_addc_co_u32_e32 v13, vcc, 0, v1, vcc
	global_store_dwordx2 v[12:13], v[8:9], off
	global_store_dwordx2 v[10:11], v[2:3], off offset:128
	v_mul_f32_e32 v2, 0x3d000000, v4
	v_pk_mul_f32 v[8:9], v[78:79], v[2:3] op_sel_hi:[1,0]
	v_pk_mul_f32 v[10:11], v[76:77], v[2:3] op_sel_hi:[1,0]
	v_pk_mul_f32 v[12:13], v[74:75], v[2:3] op_sel_hi:[1,0]
	v_max_f32_e32 v8, 0, v8
	v_max_f32_e32 v7, 0, v11
	v_max_f32_e32 v11, 0, v12
	v_mul_f32_e32 v8, v8, v8
	v_pk_mul_f32 v[14:15], v[72:73], v[2:3] op_sel_hi:[1,0]
	v_min_f32_e32 v12, 0x43e00000, v8
	v_mul_f32_e32 v8, v11, v11
	v_max_f32_e32 v3, 0, v10
	v_max_f32_e32 v4, 0, v14
	v_max_f32_e32 v10, 0, v15
	v_min_f32_e32 v11, 0x43e00000, v8
	v_max_f32_e32 v8, 0, v9
	v_mul_f32_e32 v3, v3, v3
	v_mul_f32_e32 v4, v4, v4
	v_mul_f32_e32 v7, v7, v7
	v_mul_f32_e32 v10, v10, v10
	v_mul_f32_e32 v8, v8, v8
	v_min_f32_e32 v3, 0x43e00000, v3
	v_min_f32_e32 v4, 0x43e00000, v4
	v_min_f32_e32 v7, 0x43e00000, v7
	v_min_f32_e32 v10, 0x43e00000, v10
	v_min_f32_e32 v14, 0x43e00000, v8
	v_mov_b32_e32 v8, 0
	v_mov_b32_e32 v9, 0
	v_cvt_pk_fp8_f32 v8, v3, v7
	v_cvt_pk_fp8_f32 v9, v4, v10
	v_max_f32_e32 v13, 0, v13
	v_mul_f32_e32 v3, v13, v13
	v_min_f32_e32 v3, 0x43e00000, v3
	v_cvt_pk_fp8_f32 v8, v12, v14 op_sel:[0,0,1]
	v_cvt_pk_fp8_f32 v9, v11, v3 op_sel:[0,0,1]
	v_pk_mul_f32 v[12:13], v[70:71], v[2:3] op_sel_hi:[1,0]
	v_pk_mul_f32 v[14:15], v[68:69], v[2:3] op_sel_hi:[1,0]
	v_pk_mul_f32 v[16:17], v[66:67], v[2:3] op_sel_hi:[1,0]
	v_pk_mul_f32 v[2:3], v[64:65], v[2:3] op_sel_hi:[1,0]
	v_max_f32_e32 v4, 0, v14
	v_max_f32_e32 v2, 0, v2
	v_mul_f32_e32 v2, v2, v2
	v_min_f32_e32 v7, 0x43e00000, v2
	v_max_f32_e32 v2, 0, v15
	v_max_f32_e32 v3, 0, v3
	v_mul_f32_e32 v2, v2, v2
	v_min_f32_e32 v14, 0x43e00000, v2
	v_mul_f32_e32 v2, v3, v3
	v_min_f32_e32 v15, 0x43e00000, v2
	v_max_f32_e32 v2, 0, v12
	v_max_f32_e32 v3, 0, v16
	v_mul_f32_e32 v2, v2, v2
	v_min_f32_e32 v12, 0x43e00000, v2
	v_mul_f32_e32 v2, v3, v3
	v_min_f32_e32 v16, 0x43e00000, v2
	v_max_f32_e32 v2, 0, v13
	v_mov_b32_e32 v3, 0
	v_mul_f32_e32 v4, v4, v4
	v_mul_f32_e32 v2, v2, v2
	v_cvt_pk_fp8_f32 v3, v7, v15
	v_min_f32_e32 v4, 0x43e00000, v4
	v_max_f32_e32 v13, 0, v17
	v_min_f32_e32 v17, 0x43e00000, v2
	v_mov_b32_e32 v2, 0
	v_cvt_pk_fp8_f32 v2, v4, v14
	v_mul_f32_e32 v4, v13, v13
	v_min_f32_e32 v4, 0x43e00000, v4
	v_cvt_pk_fp8_f32 v3, v16, v4 op_sel:[0,0,1]
	v_fmamk_f32 v4, v6, 0x3a000000, v190
	v_rsq_f32_e32 v4, v4
	v_cvt_pk_fp8_f32 v2, v12, v17 op_sel:[0,0,1]
	v_add_co_u32_e32 v6, vcc, s62, v0
	v_lshl_add_u64 v[10:11], v[0:1], 0, s[14:15]
	s_nop 0
	v_addc_co_u32_e32 v7, vcc, 0, v1, vcc
	global_store_dwordx2 v[6:7], v[8:9], off
	global_store_dwordx2 v[10:11], v[2:3], off offset:128
	v_mul_f32_e32 v2, 0x3d000000, v4
	v_pk_mul_f32 v[6:7], v[62:63], v[2:3] op_sel_hi:[1,0]
	v_pk_mul_f32 v[10:11], v[58:59], v[2:3] op_sel_hi:[1,0]
	v_max_f32_e32 v6, 0, v6
	v_pk_mul_f32 v[12:13], v[56:57], v[2:3] op_sel_hi:[1,0]
	v_max_f32_e32 v10, 0, v10
	v_mul_f32_e32 v6, v6, v6
; #define PG8_WAIT_V(n) asm volatile("s_waitcnt vmcnt(" #n ")" ::: "memory")
; #define PG8_BAR __builtin_amdgcn_s_barrier()
; template <class Epi, class Sched, bool ALIGN_EPI = false, bool SP2 = false, bool FP8 = false>
; __device__ __forceinline__ void gemm_phase(PG8_LAS unsigned char* lds, const Gemm g, const Sched& S, const Epi& E, int wave_id) {
;     ...
;         if (!has_next) break;
;     ...
;     PG8_WAIT_V(0);
;     if constexpr (!ALIGN_EPI) { if (wr == 0) PG8_BAR; }
;     PG8_BAR;
;     __device__ __forceinline__ void operator()(const f32x4 (&acc)[2][2][4][2], const Unit& u, int wr, int wc, int fr, int fq) const {
;     ...
;         for (int ai = 0; ai < 2; ++ai)
; #pragma unroll
;             for (int m = 0; m < 4; ++m) {
;                 const int row = row0 + ai * HALF + m * 16;
;                 const float rstd = __builtin_amdgcn_rsqf(rs[ai][m] * (1.f / DM) + EPS) * (1.f / W1_SCALE);
; #pragma unroll
;                 for (int bj = 0; bj < 2; ++bj) {
;                     f32x4 v0 = acc[ai][bj][m][0] * rstd, v1 = acc[ai][bj][m][1] * rstd;
; #pragma unroll
;                     for (int e = 0; e < 4; ++e) { const float a = fmaxf(v0[e], 0.f), b = fmaxf(v1[e], 0.f); v0[e] = fminf(a * a, 448.f); v1[e] = fminf(b * b, 448.f); }
;                     int w0 = __builtin_amdgcn_cvt_pk_fp8_f32(v0[0], v0[1], 0, false); w0 = __builtin_amdgcn_cvt_pk_fp8_f32(v0[2], v0[3], w0, true);
;                     int w1 = __builtin_amdgcn_cvt_pk_fp8_f32(v1[0], v1[1], 0, false); w1 = __builtin_amdgcn_cvt_pk_fp8_f32(v1[2], v1[3], w1, true);
;                     *(v2u*)(O + (size_t)row * FF + col0 + bj * HALF) = (v2u){(unsigned)w0, (unsigned)w1};
;                 }
	v_pk_mul_f32 v[8:9], v[60:61], v[2:3] op_sel_hi:[1,0]
	v_max_f32_e32 v4, 0, v12
	v_min_f32_e32 v12, 0x43e00000, v6
	v_mul_f32_e32 v6, v10, v10
	v_max_f32_e32 v3, 0, v8
	v_max_f32_e32 v8, 0, v9
	v_max_f32_e32 v9, 0, v13
	v_min_f32_e32 v10, 0x43e00000, v6
	v_max_f32_e32 v6, 0, v7
	v_mul_f32_e32 v3, v3, v3
	v_mul_f32_e32 v4, v4, v4
	v_mul_f32_e32 v8, v8, v8
	v_mul_f32_e32 v9, v9, v9
	v_mul_f32_e32 v6, v6, v6
	v_min_f32_e32 v3, 0x43e00000, v3
	v_min_f32_e32 v4, 0x43e00000, v4
	v_min_f32_e32 v8, 0x43e00000, v8
	v_min_f32_e32 v9, 0x43e00000, v9
	v_min_f32_e32 v13, 0x43e00000, v6
	v_mov_b32_e32 v6, 0
	v_mov_b32_e32 v7, 0
	v_cvt_pk_fp8_f32 v6, v3, v8
	v_cvt_pk_fp8_f32 v7, v4, v9
	v_max_f32_e32 v11, 0, v11
	v_mul_f32_e32 v3, v11, v11
	v_min_f32_e32 v3, 0x43e00000, v3
	v_cvt_pk_fp8_f32 v6, v12, v13 op_sel:[0,0,1]
	v_cvt_pk_fp8_f32 v7, v10, v3 op_sel:[0,0,1]
	v_pk_mul_f32 v[10:11], v[54:55], v[2:3] op_sel_hi:[1,0]
	v_pk_mul_f32 v[12:13], v[52:53], v[2:3] op_sel_hi:[1,0]
	v_pk_mul_f32 v[14:15], v[50:51], v[2:3] op_sel_hi:[1,0]
	v_pk_mul_f32 v[2:3], v[48:49], v[2:3] op_sel_hi:[1,0]
	v_max_f32_e32 v4, 0, v12
	v_max_f32_e32 v2, 0, v2
	v_mul_f32_e32 v2, v2, v2
	v_min_f32_e32 v12, 0x43e00000, v2
	v_max_f32_e32 v2, 0, v13
	v_max_f32_e32 v3, 0, v3
	v_mul_f32_e32 v2, v2, v2
	v_min_f32_e32 v13, 0x43e00000, v2
	v_mul_f32_e32 v2, v3, v3
	v_min_f32_e32 v16, 0x43e00000, v2
	v_max_f32_e32 v2, 0, v10
	v_max_f32_e32 v3, 0, v14
	v_mul_f32_e32 v2, v2, v2
	v_min_f32_e32 v10, 0x43e00000, v2
	v_mul_f32_e32 v2, v3, v3
	v_min_f32_e32 v14, 0x43e00000, v2
	v_max_f32_e32 v2, 0, v11
	v_mul_f32_e32 v4, v4, v4
	v_mul_f32_e32 v2, v2, v2
	v_mov_b32_e32 v3, 0
	v_min_f32_e32 v4, 0x43e00000, v4
	v_max_f32_e32 v11, 0, v15
	v_min_f32_e32 v15, 0x43e00000, v2
	v_mov_b32_e32 v2, 0
	v_cvt_pk_fp8_f32 v3, v12, v16
	v_cvt_pk_fp8_f32 v2, v4, v13
	v_mul_f32_e32 v4, v11, v11
	v_min_f32_e32 v4, 0x43e00000, v4
	v_cvt_pk_fp8_f32 v3, v14, v4 op_sel:[0,0,1]
	v_fmamk_f32 v4, v5, 0x3a000000, v190
	v_cvt_pk_fp8_f32 v2, v10, v15 op_sel:[0,0,1]
	v_rsq_f32_e32 v10, v4
	v_add_co_u32_e32 v4, vcc, s63, v0
	v_lshl_add_u64 v[8:9], v[0:1], 0, s[16:17]
	s_nop 0
	v_addc_co_u32_e32 v5, vcc, 0, v1, vcc
	global_store_dwordx2 v[4:5], v[6:7], off
	global_store_dwordx2 v[8:9], v[2:3], off offset:128
	v_mul_f32_e32 v2, 0x3d000000, v10
	v_pk_mul_f32 v[4:5], v[46:47], v[2:3] op_sel_hi:[1,0]
	v_pk_mul_f32 v[8:9], v[42:43], v[2:3] op_sel_hi:[1,0]
	v_max_f32_e32 v4, 0, v4
	v_pk_mul_f32 v[6:7], v[44:45], v[2:3] op_sel_hi:[1,0]
	v_pk_mul_f32 v[10:11], v[40:41], v[2:3] op_sel_hi:[1,0]
	v_max_f32_e32 v8, 0, v8
	v_mul_f32_e32 v4, v4, v4
	v_max_f32_e32 v3, 0, v6
	v_max_f32_e32 v6, 0, v10
	v_max_f32_e32 v10, 0, v11
	v_min_f32_e32 v11, 0x43e00000, v4
	v_mul_f32_e32 v4, v8, v8
	v_max_f32_e32 v7, 0, v7
	v_min_f32_e32 v8, 0x43e00000, v4
	v_max_f32_e32 v4, 0, v5
	v_mul_f32_e32 v3, v3, v3
	v_mul_f32_e32 v6, v6, v6
	v_mul_f32_e32 v7, v7, v7
	v_mul_f32_e32 v10, v10, v10
	v_mul_f32_e32 v4, v4, v4
	v_min_f32_e32 v3, 0x43e00000, v3
	v_min_f32_e32 v6, 0x43e00000, v6
	v_min_f32_e32 v7, 0x43e00000, v7
	v_min_f32_e32 v10, 0x43e00000, v10
	v_min_f32_e32 v12, 0x43e00000, v4
	v_mov_b32_e32 v4, 0
	v_mov_b32_e32 v5, 0
	v_cvt_pk_fp8_f32 v4, v3, v7
	v_cvt_pk_fp8_f32 v5, v6, v10
	v_max_f32_e32 v9, 0, v9
	v_mul_f32_e32 v3, v9, v9
	v_min_f32_e32 v3, 0x43e00000, v3
	v_cvt_pk_fp8_f32 v4, v11, v12 op_sel:[0,0,1]
	v_cvt_pk_fp8_f32 v5, v8, v3 op_sel:[0,0,1]
	v_pk_mul_f32 v[8:9], v[38:39], v[2:3] op_sel_hi:[1,0]
	v_pk_mul_f32 v[10:11], v[36:37], v[2:3] op_sel_hi:[1,0]
	v_pk_mul_f32 v[12:13], v[34:35], v[2:3] op_sel_hi:[1,0]
	v_pk_mul_f32 v[2:3], v[32:33], v[2:3] op_sel_hi:[1,0]
	v_max_f32_e32 v10, 0, v10
	v_max_f32_e32 v2, 0, v2
	v_mul_f32_e32 v2, v2, v2
	v_min_f32_e32 v14, 0x43e00000, v2
	v_max_f32_e32 v2, 0, v11
	v_max_f32_e32 v3, 0, v3
	v_mul_f32_e32 v2, v2, v2
	v_min_f32_e32 v11, 0x43e00000, v2
	v_mul_f32_e32 v2, v3, v3
	v_min_f32_e32 v15, 0x43e00000, v2
	v_max_f32_e32 v2, 0, v8
	v_max_f32_e32 v3, 0, v12
	v_mul_f32_e32 v2, v2, v2
	v_min_f32_e32 v8, 0x43e00000, v2
	v_mul_f32_e32 v2, v3, v3
	v_min_f32_e32 v12, 0x43e00000, v2
	v_max_f32_e32 v2, 0, v9
	v_mul_f32_e32 v10, v10, v10
	v_mul_f32_e32 v2, v2, v2
	v_min_f32_e32 v10, 0x43e00000, v10
	v_max_f32_e32 v9, 0, v13
	v_min_f32_e32 v13, 0x43e00000, v2
	v_mov_b32_e32 v2, 0
	v_mov_b32_e32 v3, 0
	v_cvt_pk_fp8_f32 v2, v10, v11
	v_cvt_pk_fp8_f32 v3, v14, v15
	v_mul_f32_e32 v9, v9, v9
	v_min_f32_e32 v9, 0x43e00000, v9
	v_lshl_add_u64 v[6:7], v[0:1], 0, s[18:19]
	v_cvt_pk_fp8_f32 v2, v8, v13 op_sel:[0,0,1]
	v_cvt_pk_fp8_f32 v3, v12, v9 op_sel:[0,0,1]
	v_add_co_u32_e32 v0, vcc, s64, v0
	s_nop 1
	v_addc_co_u32_e32 v1, vcc, 0, v1, vcc
	s_and_b64 vcc, exec, s[0:1]
	global_store_dwordx2 v[0:1], v[4:5], off
	global_store_dwordx2 v[6:7], v[2:3], off offset:128
	s_cbranch_vccz .LBB0_412
	s_waitcnt vmcnt(0)
	s_cmpk_gt_u32 s42, 0xff
	s_cbranch_scc1 .LBB0_423
	s_barrier
